# attention: Q rows loaded and outputs stored as full 512-byte row runs through a wave-private LDS transpose in the idle P area (8 x 16-byte stores instead of 16 x 8-byte)
# speedup vs baseline: 1.0408x; 1.0027x over previous
; #define LAS __attribute__((address_space(3)))
; __device__ __forceinline__ int opaque_tid() { int t = threadIdx.x; asm volatile("" : "+v"(t)); return t; }
; __device__ __forceinline__ void ph_attn(const Params& p, LAS unsigned char* lds) {
;     const int tid = opaque_tid(), lane = tid & 63, w = __builtin_amdgcn_readfirstlane(tid >> 6), fr = lane & 15, fq = lane >> 4;
;     unsigned char* ws = p.ws; const bf16_t* qb = (const bf16_t*)(ws + WS_A); const bf16_t* kb = (const bf16_t*)(ws + WS_KB); const bf16_t* vt = (const bf16_t*)(ws + WS_VT); bf16_t* ao = (bf16_t*)(ws + WS_B);
;     constexpr int PR = 36864;
;     LAS unsigned char* pw = lds + PR + w * 8448 + fr * 528 + fq * 8;
;     const unsigned koff = (unsigned)((tid >> 5) * 1024 + (tid & 31) * 8);
;     const unsigned voff = (unsigned)((tid >> 3) * 256 + (tid & 7) * 8);
;     LAS unsigned char* kst = lds + (tid >> 5) * 528 + (tid & 31) * 16;
;     LAS unsigned char* vst = lds + (tid >> 3) * 144 + (tid & 7) * 16;
;     const LAS unsigned char* krd = lds + fr * 528 + fq * 16;
;     const LAS unsigned char* vrd = lds + fr * 144 + fq * 16;
.LBB0_1080:
	s_cmp_lt_i32 s94, 9
	s_cselect_b64 s[0:1], -1, 0
	s_and_b64 s[4:5], s[0:1], s[4:5]
	s_andn2_b64 vcc, exec, s[4:5]
	s_cbranch_vccnz .LBB0_1110
	v_mov_b32_e32 v0, v200
	s_cmpk_gt_i32 s2, 0x43f
	s_nop 0
	v_readfirstlane_b32 s4, v0
	s_cbranch_scc1 .LBB0_1110
	s_add_u32 s6, s92, 0x11680000
	s_addc_u32 s7, s93, 0
	s_add_u32 s3, s92, 0x19c80000
	s_addc_u32 s14, s93, 0
	s_add_u32 s15, s92, 0x1a880000
	s_addc_u32 s20, s93, 0
	s_add_u32 s8, s92, 0x15780000
	s_addc_u32 s9, s93, 0
	s_ashr_i32 s4, s4, 6
	s_waitcnt lgkmcnt(0)
	v_and_b32_e32 v1, 15, v0
	s_waitcnt vmcnt(0)
	v_bfe_u32 v3, v0, 4, 2
	s_mul_i32 s5, s4, 0x2100
	v_ashrrev_i32_e32 v4, 5, v0
	v_and_b32_e32 v6, 31, v0
	v_ashrrev_i32_e32 v7, 3, v0
	v_and_b32_e32 v0, 7, v0
	s_add_i32 s10, s5, 0
	v_lshlrev_b32_e32 v11, 4, v0
	v_lshlrev_b32_e32 v0, 3, v0
	s_movk_i32 s12, 0x210
	v_mov_b32_e32 v2, s10
	s_movk_i32 s10, 0x90
	v_lshl_or_b32 v180, v7, 8, v0
	v_lshlrev_b32_e32 v0, 3, v6
	v_mad_u32_u24 v5, v1, s12, v2
	v_lshlrev_b32_e32 v2, 3, v3
	v_mul_lo_u32 v8, v4, s12
	v_mul_lo_u32 v10, v7, s10
	v_mad_u32_u24 v12, v1, s12, 0
	v_lshlrev_b32_e32 v13, 4, v3
	s_movk_i32 s10, 0xfe80
	v_lshl_or_b32 v182, v4, 10, v0
	s_lshl_b32 s21, s4, 4
	v_lshlrev_b32_e32 v4, 2, v3
	v_mov_b32_e32 v3, s5
	v_add_u32_e32 v193, v12, v13
	v_mad_i32_i24 v12, v1, s10, v12
	v_or_b32_e32 v196, s21, v1
	v_mad_u32_u24 v1, v1, s12, v3
	v_mov_b32_e32 v0, 0
	v_add3_u32 v1, v1, v13, 0
	v_add_u32_e32 v8, 0, v8
	v_lshlrev_b32_e32 v9, 4, v6
	v_add_u32_e32 v10, 0, v10
	v_mov_b32_e32 v181, v0
	v_add_u32_e32 v197, 0x9000, v1
	v_mbcnt_lo_u32_b32 v1, -1, 0
	s_mov_b32 s11, 0
	v_mov_b32_e32 v183, v0
	v_lshl_add_u64 v[184:185], v[180:181], 1, s[92:93]
	s_mov_b32 s22, 0x8000
	v_lshlrev_b32_e32 v186, 1, v2
	s_mov_b32 s23, 0x10000
	s_mov_b32 s24, 0x18000
	s_mov_b32 s25, 0x20000
	s_mov_b32 s26, 0xff61b1e6
	v_add_u32_e32 v198, v5, v2
	v_add_u32_e32 v199, v10, v11
	v_add_u32_e32 v201, v12, v13
	v_lshlrev_b32_e32 v188, 1, v4
	v_add_u32_e32 v202, v8, v9
	v_mbcnt_hi_u32_b32 v203, -1, v1
	s_mov_b32 s27, s2
	s_mov_b32 s96, 0
	v_lshrrev_b32_e32 v237, 3, v200
	v_and_b32_e32 v238, 7, v200
	v_bfe_u32 v239, v200, 4, 3
	v_xor_b32_e32 v238, v238, v239
	v_lshlrev_b32_e32 v238, 4, v238
	v_lshl_add_u32 v199, v237, 7, v238
	v_and_b32_e32 v237, 15, v200
	v_bfe_u32 v238, v200, 4, 2
	v_bfe_u32 v239, v200, 1, 3
	v_xor_b32_e32 v238, v238, v239
	v_lshlrev_b32_e32 v238, 4, v238
	v_lshl_add_u32 v201, v237, 7, v238
	v_xor_b32_e32 v239, 64, v201
	v_lshrrev_b32_e32 v237, 5, v200
	v_and_b32_e32 v238, 31, v200
	v_xor_b32_e32 v238, v238, v237
	v_lshlrev_b32_e32 v238, 4, v238
	v_lshl_add_u32 v202, v237, 9, v238
	v_and_b32_e32 v237, 15, v200
	v_bfe_u32 v238, v200, 4, 2
	v_and_b32_e32 v193, 3, v237
	v_xor_b32_e32 v238, v238, v193
	v_lshlrev_b32_e32 v238, 4, v238
	v_lshrrev_b32_e32 v193, 2, v237
	v_lshl_add_u32 v238, v193, 6, v238
	v_lshl_add_u32 v193, v237, 9, v238
	v_lshrrev_b32_e32 v237, 6, v200
	v_mul_u32_u24_e32 v237, 0x2100, v237
	v_bfe_u32 v238, v200, 5, 1
	v_mul_u32_u24_e32 v238, 0x210, v238
	v_and_b32_e32 v205, 31, v200
	v_lshlrev_b32_e32 v205, 4, v205
	v_add3_u32 v205, v205, v237, v238
	v_add_u32_e32 v205, 0x9000, v205
	v_and_b32_e32 v238, 15, v200
	v_mul_u32_u24_e32 v238, 0x210, v238
	v_bfe_u32 v206, v200, 4, 2
	v_lshlrev_b32_e32 v206, 3, v206
	v_add3_u32 v206, v206, v237, v238
	v_add_u32_e32 v206, 0x9000, v206
	s_branch .LBB0_1084

; __device__ __forceinline__ void ph_attn(const Params& p, LAS unsigned char* lds) {
;     ...
;         if (active) {
;             const bf16_t* qp = qb + (size_t)(r0 + w * 16 + fr) * D + h * 256 + fq * 8;
; #pragma unroll
;             for (int ks = 0; ks < 8; ++ks) qf[ks] = *(const bf16x8*)(qp + ks * 32);
;         }
.LBB0_1090:
	v_add_u32_e32 v190, s18, v196
	s_andn2_b64 vcc, exec, s[16:17]
	v_ashrrev_i32_e32 v191, 31, v190
	s_cbranch_vccnz .LBB0_1092
	s_add_i32 s16, s18, s21
	v_lshrrev_b32_e32 v204, 5, v203
	v_add_u32_e32 v204, s16, v204
	v_lshlrev_b32_e32 v204, 11, v204
	s_lshl_b32 s16, s5, 9
	v_and_b32_e32 v2, 31, v203
	v_lshlrev_b32_e32 v2, 4, v2
	v_add3_u32 v204, v204, s16, v2
	s_cmp_eq_u32 s96, 1
	s_cbranch_scc1 .Lpf_skipq
	v_mov_b32_e32 v32, v204
	v_add_u32_e32 v28, 0x1000, v204
	v_add_u32_e32 v24, 0x2000, v204
	v_add_u32_e32 v20, 0x3000, v204
	v_add_u32_e32 v16, 0x4000, v204
	v_add_u32_e32 v12, 0x5000, v204
	v_add_u32_e32 v8, 0x6000, v204
	v_add_u32_e32 v4, 0x7000, v204
	global_load_dwordx4 v[32:35], v32, s[6:7]
	global_load_dwordx4 v[28:31], v28, s[6:7]
	global_load_dwordx4 v[24:27], v24, s[6:7]
	global_load_dwordx4 v[20:23], v20, s[6:7]
	global_load_dwordx4 v[16:19], v16, s[6:7]
	global_load_dwordx4 v[12:15], v12, s[6:7]
	global_load_dwordx4 v[8:11], v8, s[6:7]
	global_load_dwordx4 v[4:7], v4, s[6:7]

; #define LAS __attribute__((address_space(3)))
; #define LOADK(i) do { _Pragma("unroll") for (int j = 0; j < 4; ++j) st[j] = *(const u32x4*)(kbase + ((i) * 64 + j * 16) * 1024 + koff); } while (0)
; #define LOADV(i) do { _Pragma("unroll") for (int j = 0; j < 4; ++j) st[j] = *(const u32x4*)(vbase + (j * 64 * 256 + (i) * 64) + voff); } while (0)
; #define STOREK() do { _Pragma("unroll") for (int j = 0; j < 4; ++j) *(LAS u32x4*)(kst + j * 16 * 528) = st[j]; } while (0)
; __device__ __forceinline__ void ph_attn(const Params& p, LAS unsigned char* lds) {
;     ...
;         u32x4 st[4];
;         const bf16_t* kbase = kb + (size_t)kvb * 256 * 1024 + h * 256; const bf16_t* vbase = vt + ((size_t)kvb * 1024 + h * 256) * 256;
;     ...
;         f32x4 sc[16];
;         LOADK(0);
; #pragma unroll
;         for (int i = 0; i < 4; ++i) {
;             __syncthreads(); STOREK(); __syncthreads();
;             if (i < 3) LOADK(i + 1); else LOADV(0);
;             if (active) {
; #pragma unroll
;                 for (int sub = 0; sub < 4; ++sub) {
;                     f32x4 a = {0.f, 0.f, 0.f, 0.f};
; #pragma unroll
;                     for (int ks = 0; ks < 8; ++ks) {
;                         const bf16x8 kf = *(const LAS bf16x8*)(krd + sub * 16 * 528 + ks * 64);
;                         a = __builtin_amdgcn_mfma_f32_16x16x32_bf16(kf, qf[ks], a, 0, 0, 0);
;                     }
;                     sc[i * 4 + sub] = a;
;                 }
;             }
;         }
.LBB0_1092:
	s_ashr_i32 s5, s4, 31
	s_lshl_b64 s[16:17], s[4:5], 19
	s_add_u32 s18, s3, s16
	s_addc_u32 s19, s14, s17
	s_lshl_b64 s[4:5], s[10:11], 1
	s_add_u32 s98, s18, s4
	s_addc_u32 s99, s19, s5
	s_lshl_b64 s[18:19], s[10:11], 9
	s_add_u32 s100, s15, s16
	s_addc_u32 s101, s20, s17
	s_add_u32 s100, s100, s18
	s_addc_u32 s101, s101, s19
	v_lshlrev_b32_e32 v237, 1, v182
	v_lshlrev_b32_e32 v238, 1, v180
	v_xor_b32_e32 v124, 64, v193
	v_xor_b32_e32 v125, 0x80, v193
	v_xor_b32_e32 v126, 0xc0, v193
	s_cmp_eq_u32 s96, 1
	s_cbranch_scc1 .Lpf_start
	v_mov_b32_e32 v100, v237
	v_add_u32_e32 v104, 0x8000, v237
	v_add_u32_e32 v108, 0x10000, v237
	v_add_u32_e32 v112, 0x18000, v237
	global_load_dwordx4 v[100:103], v100, s[98:99]
	global_load_dwordx4 v[104:107], v104, s[98:99]
	global_load_dwordx4 v[108:111], v108, s[98:99]
	global_load_dwordx4 v[112:115], v112, s[98:99]
	v_add_u32_e32 v240, 0x20000, v237
	v_add_u32_e32 v244, 0x28000, v237
	v_add_u32_e32 v248, 0x30000, v237
	v_add_u32_e32 v252, 0x38000, v237
	global_load_dwordx4 v[240:243], v240, s[98:99]
	global_load_dwordx4 v[244:247], v244, s[98:99]
	global_load_dwordx4 v[248:251], v248, s[98:99]
	global_load_dwordx4 v[252:255], v252, s[98:99]
	s_barrier
	s_waitcnt vmcnt(7)
	ds_write_b128 v202, v[100:103]
	s_waitcnt vmcnt(6)
	ds_write_b128 v202, v[104:107] offset:8192
	s_waitcnt vmcnt(5)
	ds_write_b128 v202, v[108:111] offset:16384
	s_waitcnt vmcnt(4)
	ds_write_b128 v202, v[112:115] offset:24576
	s_branch .Lpf_join0
	.Lpf_start:
	s_barrier
	s_waitcnt vmcnt(15)
	ds_write_b128 v202, v[100:103]
	s_waitcnt vmcnt(14)
	ds_write_b128 v202, v[104:107] offset:8192
	s_waitcnt vmcnt(13)
	ds_write_b128 v202, v[108:111] offset:16384
	s_waitcnt vmcnt(12)
	ds_write_b128 v202, v[112:115] offset:24576
	.Lpf_join0:
	v_add_u32_e32 v100, 0x40000, v237
	v_add_u32_e32 v104, 0x48000, v237
	v_add_u32_e32 v108, 0x50000, v237
	v_add_u32_e32 v112, 0x58000, v237
	s_waitcnt lgkmcnt(0)
	s_barrier
	global_load_dwordx4 v[100:103], v100, s[98:99]
	global_load_dwordx4 v[104:107], v104, s[98:99]
	global_load_dwordx4 v[108:111], v108, s[98:99]
	global_load_dwordx4 v[112:115], v112, s[98:99]
	s_and_b64 vcc, exec, s[12:13]
	s_cbranch_vccz .LBB0_1094
	ds_write_b128 v205, v[32:35]
	ds_write_b128 v205, v[28:31] offset:1056
	ds_write_b128 v205, v[24:27] offset:2112
	ds_write_b128 v205, v[20:23] offset:3168
	ds_write_b128 v205, v[16:19] offset:4224
	ds_write_b128 v205, v[12:15] offset:5280
	ds_write_b128 v205, v[8:11] offset:6336
	ds_write_b128 v205, v[4:7] offset:7392
	s_waitcnt lgkmcnt(0)
	ds_read_b128 v[32:35], v197
	ds_read_b128 v[28:31], v197 offset:64
	ds_read_b128 v[24:27], v197 offset:128
	ds_read_b128 v[20:23], v197 offset:192
	ds_read_b128 v[16:19], v197 offset:256
	ds_read_b128 v[12:15], v197 offset:320
	ds_read_b128 v[8:11], v197 offset:384
	ds_read_b128 v[4:7], v197 offset:448
	s_waitcnt lgkmcnt(0)
	ds_read_b128 v[128:131], v193
	ds_read_b128 v[132:135], v193 offset:8192
	ds_read_b128 v[136:139], v193 offset:16384
	ds_read_b128 v[140:143], v193 offset:24576
	ds_read_b128 v[144:147], v124
	ds_read_b128 v[148:151], v124 offset:8192
	ds_read_b128 v[152:155], v124 offset:16384
	ds_read_b128 v[156:159], v124 offset:24576
	s_waitcnt lgkmcnt(7)
	v_mfma_f32_16x16x32_bf16 v[48:51], v[128:131], v[32:35], 0
	ds_read_b128 v[160:163], v125
	s_waitcnt lgkmcnt(7)
	v_mfma_f32_16x16x32_bf16 v[64:67], v[132:135], v[32:35], 0
	ds_read_b128 v[164:167], v125 offset:8192
	s_waitcnt lgkmcnt(7)
	v_mfma_f32_16x16x32_bf16 v[80:83], v[136:139], v[32:35], 0
	ds_read_b128 v[168:171], v125 offset:16384
	s_waitcnt lgkmcnt(7)
	v_mfma_f32_16x16x32_bf16 v[96:99], v[140:143], v[32:35], 0
	ds_read_b128 v[172:175], v125 offset:24576
	s_waitcnt lgkmcnt(7)
	v_mfma_f32_16x16x32_bf16 v[48:51], v[144:147], v[28:31], v[48:51]
	ds_read_b128 v[176:179], v126
	s_waitcnt lgkmcnt(7)
	v_mfma_f32_16x16x32_bf16 v[64:67], v[148:151], v[28:31], v[64:67]
	ds_read_b128 v[128:131], v126 offset:8192
	s_waitcnt lgkmcnt(7)
	v_mfma_f32_16x16x32_bf16 v[80:83], v[152:155], v[28:31], v[80:83]
	ds_read_b128 v[132:135], v126 offset:16384
	s_waitcnt lgkmcnt(7)
	v_mfma_f32_16x16x32_bf16 v[96:99], v[156:159], v[28:31], v[96:99]
	ds_read_b128 v[136:139], v126 offset:24576
	s_waitcnt lgkmcnt(7)
	v_mfma_f32_16x16x32_bf16 v[48:51], v[160:163], v[24:27], v[48:51]
	ds_read_b128 v[140:143], v193 offset:256
	s_waitcnt lgkmcnt(7)
	v_mfma_f32_16x16x32_bf16 v[64:67], v[164:167], v[24:27], v[64:67]
	ds_read_b128 v[144:147], v193 offset:8448
	s_waitcnt lgkmcnt(7)
	v_mfma_f32_16x16x32_bf16 v[80:83], v[168:171], v[24:27], v[80:83]
	ds_read_b128 v[148:151], v193 offset:16640
	s_waitcnt lgkmcnt(7)
	v_mfma_f32_16x16x32_bf16 v[96:99], v[172:175], v[24:27], v[96:99]
	ds_read_b128 v[152:155], v193 offset:24832
	s_waitcnt lgkmcnt(7)
	v_mfma_f32_16x16x32_bf16 v[48:51], v[176:179], v[20:23], v[48:51]
	ds_read_b128 v[156:159], v124 offset:256
	s_waitcnt lgkmcnt(7)
	v_mfma_f32_16x16x32_bf16 v[64:67], v[128:131], v[20:23], v[64:67]
	ds_read_b128 v[160:163], v124 offset:8448
	s_waitcnt lgkmcnt(7)
	v_mfma_f32_16x16x32_bf16 v[80:83], v[132:135], v[20:23], v[80:83]
	ds_read_b128 v[164:167], v124 offset:16640
	s_waitcnt lgkmcnt(7)
	v_mfma_f32_16x16x32_bf16 v[96:99], v[136:139], v[20:23], v[96:99]
	ds_read_b128 v[168:171], v124 offset:24832
	s_waitcnt lgkmcnt(7)
	v_mfma_f32_16x16x32_bf16 v[48:51], v[140:143], v[16:19], v[48:51]
	ds_read_b128 v[172:175], v125 offset:256
	s_waitcnt lgkmcnt(7)
	v_mfma_f32_16x16x32_bf16 v[64:67], v[144:147], v[16:19], v[64:67]
	ds_read_b128 v[176:179], v125 offset:8448
	s_waitcnt lgkmcnt(7)
	v_mfma_f32_16x16x32_bf16 v[80:83], v[148:151], v[16:19], v[80:83]
	ds_read_b128 v[128:131], v125 offset:16640
	s_waitcnt lgkmcnt(7)
	v_mfma_f32_16x16x32_bf16 v[96:99], v[152:155], v[16:19], v[96:99]
	ds_read_b128 v[132:135], v125 offset:24832
	s_waitcnt lgkmcnt(7)
	v_mfma_f32_16x16x32_bf16 v[48:51], v[156:159], v[12:15], v[48:51]
	ds_read_b128 v[136:139], v126 offset:256
	s_waitcnt lgkmcnt(7)
	v_mfma_f32_16x16x32_bf16 v[64:67], v[160:163], v[12:15], v[64:67]
	ds_read_b128 v[140:143], v126 offset:8448
	s_waitcnt lgkmcnt(7)
	v_mfma_f32_16x16x32_bf16 v[80:83], v[164:167], v[12:15], v[80:83]
	ds_read_b128 v[144:147], v126 offset:16640
	s_waitcnt lgkmcnt(7)
	v_mfma_f32_16x16x32_bf16 v[96:99], v[168:171], v[12:15], v[96:99]
	ds_read_b128 v[148:151], v126 offset:24832
	s_waitcnt lgkmcnt(7)
	v_mfma_f32_16x16x32_bf16 v[48:51], v[172:175], v[8:11], v[48:51]
	s_waitcnt lgkmcnt(6)
	v_mfma_f32_16x16x32_bf16 v[64:67], v[176:179], v[8:11], v[64:67]
	s_waitcnt lgkmcnt(5)
	v_mfma_f32_16x16x32_bf16 v[80:83], v[128:131], v[8:11], v[80:83]
	s_waitcnt lgkmcnt(4)
	v_mfma_f32_16x16x32_bf16 v[96:99], v[132:135], v[8:11], v[96:99]
	s_waitcnt lgkmcnt(3)
	v_mfma_f32_16x16x32_bf16 v[48:51], v[136:139], v[4:7], v[48:51]
	s_waitcnt lgkmcnt(2)
	v_mfma_f32_16x16x32_bf16 v[64:67], v[140:143], v[4:7], v[64:67]
	s_waitcnt lgkmcnt(1)
	v_mfma_f32_16x16x32_bf16 v[80:83], v[144:147], v[4:7], v[80:83]
	s_waitcnt lgkmcnt(0)
	v_mfma_f32_16x16x32_bf16 v[96:99], v[148:151], v[4:7], v[96:99]
; #define LAS __attribute__((address_space(3)))
; #define LOADK(i) do { _Pragma("unroll") for (int j = 0; j < 4; ++j) st[j] = *(const u32x4*)(kbase + ((i) * 64 + j * 16) * 1024 + koff); } while (0)
; #define LOADV(i) do { _Pragma("unroll") for (int j = 0; j < 4; ++j) st[j] = *(const u32x4*)(vbase + (j * 64 * 256 + (i) * 64) + voff); } while (0)
; #define STOREK() do { _Pragma("unroll") for (int j = 0; j < 4; ++j) *(LAS u32x4*)(kst + j * 16 * 528) = st[j]; } while (0)
; __device__ __forceinline__ void ph_attn(const Params& p, LAS unsigned char* lds) {
;     ...
;         for (int i = 0; i < 4; ++i) {
;             __syncthreads(); STOREK(); __syncthreads();
;             if (i < 3) LOADK(i + 1); else LOADV(0);
;             if (active) {
; #pragma unroll
;                 for (int sub = 0; sub < 4; ++sub) {
;                     f32x4 a = {0.f, 0.f, 0.f, 0.f};
; #pragma unroll
;                     for (int ks = 0; ks < 8; ++ks) {
;                         const bf16x8 kf = *(const LAS bf16x8*)(krd + sub * 16 * 528 + ks * 64);
;                         a = __builtin_amdgcn_mfma_f32_16x16x32_bf16(kf, qf[ks], a, 0, 0, 0);
;                     }
;                     sc[i * 4 + sub] = a;
;                 }
;             }
;         }
.LBB0_1094:
	s_barrier
	s_cmp_eq_u32 s96, 1
	s_cbranch_scc1 .Lpf_v0
	s_waitcnt vmcnt(7)
	ds_write_b128 v202, v[240:243]
	s_waitcnt vmcnt(6)
	ds_write_b128 v202, v[244:247] offset:8192
	s_waitcnt vmcnt(5)
	ds_write_b128 v202, v[248:251] offset:16384
	s_waitcnt vmcnt(4)
	ds_write_b128 v202, v[252:255] offset:24576
	s_branch .Lpf_j0
	.Lpf_v0:
	s_waitcnt vmcnt(15)
	ds_write_b128 v202, v[240:243]
	s_waitcnt vmcnt(14)
	ds_write_b128 v202, v[244:247] offset:8192
	s_waitcnt vmcnt(13)
	ds_write_b128 v202, v[248:251] offset:16384
	s_waitcnt vmcnt(12)
	ds_write_b128 v202, v[252:255] offset:24576
	.Lpf_j0:
	v_add_u32_e32 v240, 0x60000, v237
	v_add_u32_e32 v244, 0x68000, v237
	v_add_u32_e32 v248, 0x70000, v237
	v_add_u32_e32 v252, 0x78000, v237
	s_waitcnt lgkmcnt(0)
	s_barrier
	global_load_dwordx4 v[240:243], v240, s[98:99]
	global_load_dwordx4 v[244:247], v244, s[98:99]
	global_load_dwordx4 v[248:251], v248, s[98:99]
	global_load_dwordx4 v[252:255], v252, s[98:99]
	v_cndmask_b32_e64 v1, 0, 1, s[12:13]
	v_cmp_ne_u32_e64 s[4:5], 1, v1
	s_andn2_b64 vcc, exec, s[12:13]
	s_cbranch_vccnz .LBB0_1096
	ds_read_b128 v[128:131], v193
	ds_read_b128 v[132:135], v193 offset:8192
	ds_read_b128 v[136:139], v193 offset:16384
	ds_read_b128 v[140:143], v193 offset:24576
	ds_read_b128 v[144:147], v124
	ds_read_b128 v[148:151], v124 offset:8192
	ds_read_b128 v[152:155], v124 offset:16384
	ds_read_b128 v[156:159], v124 offset:24576
	s_waitcnt lgkmcnt(7)
	v_mfma_f32_16x16x32_bf16 v[44:47], v[128:131], v[32:35], 0
	ds_read_b128 v[160:163], v125
	s_waitcnt lgkmcnt(7)
	v_mfma_f32_16x16x32_bf16 v[60:63], v[132:135], v[32:35], 0
	ds_read_b128 v[164:167], v125 offset:8192
	s_waitcnt lgkmcnt(7)
	v_mfma_f32_16x16x32_bf16 v[76:79], v[136:139], v[32:35], 0
	ds_read_b128 v[168:171], v125 offset:16384
	s_waitcnt lgkmcnt(7)
	v_mfma_f32_16x16x32_bf16 v[92:95], v[140:143], v[32:35], 0
	ds_read_b128 v[172:175], v125 offset:24576
	s_waitcnt lgkmcnt(7)
	v_mfma_f32_16x16x32_bf16 v[44:47], v[144:147], v[28:31], v[44:47]
	ds_read_b128 v[176:179], v126
	s_waitcnt lgkmcnt(7)
	v_mfma_f32_16x16x32_bf16 v[60:63], v[148:151], v[28:31], v[60:63]
	ds_read_b128 v[128:131], v126 offset:8192
	s_waitcnt lgkmcnt(7)
	v_mfma_f32_16x16x32_bf16 v[76:79], v[152:155], v[28:31], v[76:79]
	ds_read_b128 v[132:135], v126 offset:16384
	s_waitcnt lgkmcnt(7)
	v_mfma_f32_16x16x32_bf16 v[92:95], v[156:159], v[28:31], v[92:95]
	ds_read_b128 v[136:139], v126 offset:24576
	s_waitcnt lgkmcnt(7)
	v_mfma_f32_16x16x32_bf16 v[44:47], v[160:163], v[24:27], v[44:47]
	ds_read_b128 v[140:143], v193 offset:256
	s_waitcnt lgkmcnt(7)
	v_mfma_f32_16x16x32_bf16 v[60:63], v[164:167], v[24:27], v[60:63]
	ds_read_b128 v[144:147], v193 offset:8448
	s_waitcnt lgkmcnt(7)
	v_mfma_f32_16x16x32_bf16 v[76:79], v[168:171], v[24:27], v[76:79]
	ds_read_b128 v[148:151], v193 offset:16640
	s_waitcnt lgkmcnt(7)
	v_mfma_f32_16x16x32_bf16 v[92:95], v[172:175], v[24:27], v[92:95]
	ds_read_b128 v[152:155], v193 offset:24832
	s_waitcnt lgkmcnt(7)
	v_mfma_f32_16x16x32_bf16 v[44:47], v[176:179], v[20:23], v[44:47]
	ds_read_b128 v[156:159], v124 offset:256
	s_waitcnt lgkmcnt(7)
	v_mfma_f32_16x16x32_bf16 v[60:63], v[128:131], v[20:23], v[60:63]
	ds_read_b128 v[160:163], v124 offset:8448
	s_waitcnt lgkmcnt(7)
	v_mfma_f32_16x16x32_bf16 v[76:79], v[132:135], v[20:23], v[76:79]
	ds_read_b128 v[164:167], v124 offset:16640
	s_waitcnt lgkmcnt(7)
	v_mfma_f32_16x16x32_bf16 v[92:95], v[136:139], v[20:23], v[92:95]
	ds_read_b128 v[168:171], v124 offset:24832
	s_waitcnt lgkmcnt(7)
	v_mfma_f32_16x16x32_bf16 v[44:47], v[140:143], v[16:19], v[44:47]
	ds_read_b128 v[172:175], v125 offset:256
	s_waitcnt lgkmcnt(7)
	v_mfma_f32_16x16x32_bf16 v[60:63], v[144:147], v[16:19], v[60:63]
	ds_read_b128 v[176:179], v125 offset:8448
	s_waitcnt lgkmcnt(7)
	v_mfma_f32_16x16x32_bf16 v[76:79], v[148:151], v[16:19], v[76:79]
	ds_read_b128 v[128:131], v125 offset:16640
	s_waitcnt lgkmcnt(7)
	v_mfma_f32_16x16x32_bf16 v[92:95], v[152:155], v[16:19], v[92:95]
	ds_read_b128 v[132:135], v125 offset:24832
	s_waitcnt lgkmcnt(7)
	v_mfma_f32_16x16x32_bf16 v[44:47], v[156:159], v[12:15], v[44:47]
	ds_read_b128 v[136:139], v126 offset:256
	s_waitcnt lgkmcnt(7)
	v_mfma_f32_16x16x32_bf16 v[60:63], v[160:163], v[12:15], v[60:63]
	ds_read_b128 v[140:143], v126 offset:8448
	s_waitcnt lgkmcnt(7)
	v_mfma_f32_16x16x32_bf16 v[76:79], v[164:167], v[12:15], v[76:79]
	ds_read_b128 v[144:147], v126 offset:16640
	s_waitcnt lgkmcnt(7)
	v_mfma_f32_16x16x32_bf16 v[92:95], v[168:171], v[12:15], v[92:95]
	ds_read_b128 v[148:151], v126 offset:24832
	s_waitcnt lgkmcnt(7)
	v_mfma_f32_16x16x32_bf16 v[44:47], v[172:175], v[8:11], v[44:47]
	s_waitcnt lgkmcnt(6)
	v_mfma_f32_16x16x32_bf16 v[60:63], v[176:179], v[8:11], v[60:63]
	s_waitcnt lgkmcnt(5)
	v_mfma_f32_16x16x32_bf16 v[76:79], v[128:131], v[8:11], v[76:79]
	s_waitcnt lgkmcnt(4)
	v_mfma_f32_16x16x32_bf16 v[92:95], v[132:135], v[8:11], v[92:95]
	s_waitcnt lgkmcnt(3)
	v_mfma_f32_16x16x32_bf16 v[44:47], v[136:139], v[4:7], v[44:47]
	s_waitcnt lgkmcnt(2)
	v_mfma_f32_16x16x32_bf16 v[60:63], v[140:143], v[4:7], v[60:63]
	s_waitcnt lgkmcnt(1)
	v_mfma_f32_16x16x32_bf16 v[76:79], v[144:147], v[4:7], v[76:79]
	s_waitcnt lgkmcnt(0)
	v_mfma_f32_16x16x32_bf16 v[92:95], v[148:151], v[4:7], v[92:95]

; #define LAS __attribute__((address_space(3)))
; #define LOADV(i) do { _Pragma("unroll") for (int j = 0; j < 4; ++j) st[j] = *(const u32x4*)(vbase + (j * 64 * 256 + (i) * 64) + voff); } while (0)
; #define STOREV() do { _Pragma("unroll") for (int j = 0; j < 4; ++j) *(LAS u32x4*)(vst + j * 64 * 144) = st[j]; } while (0)
; __device__ __forceinline__ void ph_attn(const Params& p, LAS unsigned char* lds) {
;     ...
;         if (active) {
;             const bf16_t* qp = qb + (size_t)(r0 + w * 16 + fr) * D + h * 256 + fq * 8;
; #pragma unroll
;             for (int ks = 0; ks < 8; ++ks) qf[ks] = *(const bf16x8*)(qp + ks * 32);
;     ...
; #pragma unroll 1
;         for (int i = 0; i < 4; ++i) {
;             __syncthreads(); STOREV(); __syncthreads();
;             if (i < 3) LOADV(i + 1);
;             if (active) {
; #pragma unroll
;                 for (int ks = 0; ks < 2; ++ks) {
;                     const bf16x8 pf = *(const LAS bf16x8*)(pw + fq * 8 + i * 128 + ks * 64);
; #pragma unroll
;                     for (int dt = 0; dt < 16; ++dt) {
;                         const bf16x8 vf = *(const LAS bf16x8*)(vrd + dt * 16 * 144 + ks * 64);
;                         oa[dt] = __builtin_amdgcn_mfma_f32_16x16x32_bf16(vf, pf, oa[dt], 0, 0, 0);
;                     }
;                 }
;             }
;         }
.Lat_pv1:
	s_waitcnt lgkmcnt(0)
	s_barrier
	s_waitcnt vmcnt(7)
	ds_write_b128 v199, v[240:243]
	s_waitcnt vmcnt(6)
	ds_write_b128 v199, v[244:247] offset:8192
	s_waitcnt vmcnt(5)
	ds_write_b128 v199, v[248:251] offset:16384
	s_waitcnt vmcnt(4)
	ds_write_b128 v199, v[252:255] offset:24576
	v_mov_b32_e32 v240, v238
	v_add_u32_e32 v244, 0x8000, v238
	v_add_u32_e32 v248, 0x10000, v238
	v_add_u32_e32 v252, 0x18000, v238
	s_waitcnt lgkmcnt(0)
	s_barrier
	global_load_dwordx4 v[240:243], v240, s[100:101] offset:384
	global_load_dwordx4 v[244:247], v244, s[100:101] offset:384
	global_load_dwordx4 v[248:251], v248, s[100:101] offset:384
	global_load_dwordx4 v[252:255], v252, s[100:101] offset:384
	s_add_i32 s97, s27, s34
	s_cmpk_lt_i32 s97, 0x400
	s_cselect_b32 s96, 1, 0
	s_cmpk_lg_i32 s34, 0x100
	s_cselect_b32 s96, 0, s96
	s_cmp_eq_u32 s96, 0
	s_cbranch_scc1 .Lpf_noq
	v_add_u32_e32 v32, 0x1000000, v204
	v_add_u32_e32 v28, 0x1001000, v204
	v_add_u32_e32 v24, 0x1002000, v204
	v_add_u32_e32 v20, 0x1003000, v204
	v_add_u32_e32 v16, 0x1004000, v204
	v_add_u32_e32 v12, 0x1005000, v204
	v_add_u32_e32 v8, 0x1006000, v204
	v_add_u32_e32 v4, 0x1007000, v204
	global_load_dwordx4 v[32:35], v32, s[6:7]
	global_load_dwordx4 v[28:31], v28, s[6:7]
	global_load_dwordx4 v[24:27], v24, s[6:7]
	global_load_dwordx4 v[20:23], v20, s[6:7]
	global_load_dwordx4 v[16:19], v16, s[6:7]
	global_load_dwordx4 v[12:15], v12, s[6:7]
	global_load_dwordx4 v[8:11], v8, s[6:7]
	global_load_dwordx4 v[4:7], v4, s[6:7]
	.Lpf_noq:
	s_and_b64 vcc, exec, s[4:5]
	s_cbranch_vccnz .Lat_pv2
	ds_read_b128 v[208:211], v187 offset:128
	ds_read_b128 v[212:215], v187 offset:192
	ds_read_b128 v[36:39], v201
	ds_read_b128 v[40:43], v201 offset:2048
	ds_read_b128 v[44:47], v201 offset:4096
	ds_read_b128 v[48:51], v201 offset:6144
	ds_read_b128 v[52:55], v201 offset:8192
	ds_read_b128 v[56:59], v201 offset:10240
	ds_read_b128 v[60:63], v201 offset:12288
	ds_read_b128 v[64:67], v201 offset:14336
	s_waitcnt lgkmcnt(7)
	v_mfma_f32_16x16x32_bf16 v[176:179], v[36:39], v[208:211], v[176:179]
	ds_read_b128 v[68:71], v201 offset:16384
	s_waitcnt lgkmcnt(7)
	v_mfma_f32_16x16x32_bf16 v[172:175], v[40:43], v[208:211], v[172:175]
	ds_read_b128 v[72:75], v201 offset:18432
	s_waitcnt lgkmcnt(7)
	v_mfma_f32_16x16x32_bf16 v[168:171], v[44:47], v[208:211], v[168:171]
	ds_read_b128 v[76:79], v201 offset:20480
	s_waitcnt lgkmcnt(7)
	v_mfma_f32_16x16x32_bf16 v[164:167], v[48:51], v[208:211], v[164:167]
	ds_read_b128 v[80:83], v201 offset:22528
	s_waitcnt lgkmcnt(7)
	v_mfma_f32_16x16x32_bf16 v[160:163], v[52:55], v[208:211], v[160:163]
	ds_read_b128 v[84:87], v201 offset:24576
	s_waitcnt lgkmcnt(7)
	v_mfma_f32_16x16x32_bf16 v[156:159], v[56:59], v[208:211], v[156:159]
	ds_read_b128 v[88:91], v201 offset:26624
	s_waitcnt lgkmcnt(7)
	v_mfma_f32_16x16x32_bf16 v[152:155], v[60:63], v[208:211], v[152:155]
	ds_read_b128 v[92:95], v201 offset:28672
	s_waitcnt lgkmcnt(7)
	v_mfma_f32_16x16x32_bf16 v[148:151], v[64:67], v[208:211], v[148:151]
	ds_read_b128 v[96:99], v201 offset:30720
	s_waitcnt lgkmcnt(7)
	v_mfma_f32_16x16x32_bf16 v[144:147], v[68:71], v[208:211], v[144:147]
	ds_read_b128 v[36:39], v239
	s_waitcnt lgkmcnt(7)
	v_mfma_f32_16x16x32_bf16 v[140:143], v[72:75], v[208:211], v[140:143]
	ds_read_b128 v[40:43], v239 offset:2048
	s_waitcnt lgkmcnt(7)
	v_mfma_f32_16x16x32_bf16 v[136:139], v[76:79], v[208:211], v[136:139]
	ds_read_b128 v[44:47], v239 offset:4096
	s_waitcnt lgkmcnt(7)
	v_mfma_f32_16x16x32_bf16 v[132:135], v[80:83], v[208:211], v[132:135]
	ds_read_b128 v[48:51], v239 offset:6144
	s_waitcnt lgkmcnt(7)
	v_mfma_f32_16x16x32_bf16 v[128:131], v[84:87], v[208:211], v[128:131]
	ds_read_b128 v[52:55], v239 offset:8192
	s_waitcnt lgkmcnt(7)
	v_mfma_f32_16x16x32_bf16 v[124:127], v[88:91], v[208:211], v[124:127]
	ds_read_b128 v[56:59], v239 offset:10240
	s_waitcnt lgkmcnt(7)
	v_mfma_f32_16x16x32_bf16 v[120:123], v[92:95], v[208:211], v[120:123]
	ds_read_b128 v[60:63], v239 offset:12288
	s_waitcnt lgkmcnt(7)
	v_mfma_f32_16x16x32_bf16 v[116:119], v[96:99], v[208:211], v[116:119]
	ds_read_b128 v[64:67], v239 offset:14336
	s_waitcnt lgkmcnt(7)
	v_mfma_f32_16x16x32_bf16 v[176:179], v[36:39], v[212:215], v[176:179]
	ds_read_b128 v[68:71], v239 offset:16384
	s_waitcnt lgkmcnt(7)
	v_mfma_f32_16x16x32_bf16 v[172:175], v[40:43], v[212:215], v[172:175]
	ds_read_b128 v[72:75], v239 offset:18432
	s_waitcnt lgkmcnt(7)
	v_mfma_f32_16x16x32_bf16 v[168:171], v[44:47], v[212:215], v[168:171]
	ds_read_b128 v[76:79], v239 offset:20480
	s_waitcnt lgkmcnt(7)
	v_mfma_f32_16x16x32_bf16 v[164:167], v[48:51], v[212:215], v[164:167]
	ds_read_b128 v[80:83], v239 offset:22528
	s_waitcnt lgkmcnt(7)
	v_mfma_f32_16x16x32_bf16 v[160:163], v[52:55], v[212:215], v[160:163]
	ds_read_b128 v[84:87], v239 offset:24576
	s_waitcnt lgkmcnt(7)
	v_mfma_f32_16x16x32_bf16 v[156:159], v[56:59], v[212:215], v[156:159]
	ds_read_b128 v[88:91], v239 offset:26624
	s_waitcnt lgkmcnt(7)
	v_mfma_f32_16x16x32_bf16 v[152:155], v[60:63], v[212:215], v[152:155]
	ds_read_b128 v[92:95], v239 offset:28672
	s_waitcnt lgkmcnt(7)
	v_mfma_f32_16x16x32_bf16 v[148:151], v[64:67], v[212:215], v[148:151]
	ds_read_b128 v[96:99], v239 offset:30720
	s_waitcnt lgkmcnt(7)
	v_mfma_f32_16x16x32_bf16 v[144:147], v[68:71], v[212:215], v[144:147]
	s_waitcnt lgkmcnt(6)
	v_mfma_f32_16x16x32_bf16 v[140:143], v[72:75], v[212:215], v[140:143]
	s_waitcnt lgkmcnt(5)
	v_mfma_f32_16x16x32_bf16 v[136:139], v[76:79], v[212:215], v[136:139]
	s_waitcnt lgkmcnt(4)
	v_mfma_f32_16x16x32_bf16 v[132:135], v[80:83], v[212:215], v[132:135]
	s_waitcnt lgkmcnt(3)
	v_mfma_f32_16x16x32_bf16 v[128:131], v[84:87], v[212:215], v[128:131]
	s_waitcnt lgkmcnt(2)
	v_mfma_f32_16x16x32_bf16 v[124:127], v[88:91], v[212:215], v[124:127]
	s_waitcnt lgkmcnt(1)
	v_mfma_f32_16x16x32_bf16 v[120:123], v[92:95], v[212:215], v[120:123]
	s_waitcnt lgkmcnt(0)
	v_mfma_f32_16x16x32_bf16 v[116:119], v[96:99], v[212:215], v[116:119]

; __device__ __forceinline__ unsigned cvt_pk_bf16(float lo, float hi) { f32x2 f = {lo, hi}; bf16x2_t v = __builtin_convertvector(f, bf16x2_t); return __builtin_bit_cast(unsigned, v); }
; __device__ __forceinline__ void ph_attn(const Params& p, LAS unsigned char* lds) {
;     ...
;         if (active) {
;             bf16_t* dst = ao + (size_t)(r0 + w * 16 + fr) * D + h * 256 + fq * 4;
; #pragma unroll
;             for (int dt = 0; dt < 16; ++dt) { u32x2 wv; wv.x = cvt_pk_bf16(oa[dt][0] * linv, oa[dt][1] * linv); wv.y = cvt_pk_bf16(oa[dt][2] * linv, oa[dt][3] * linv); *(u32x2*)(dst + dt * 16) = wv; }
;         }
.LBB0_1108:
	s_and_b64 vcc, exec, s[12:13]
	s_cbranch_vccz .LBB0_1083
	v_pk_mul_f32 v[36:37], v[192:193], v[176:177] op_sel_hi:[0,1]
	v_pk_mul_f32 v[38:39], v[192:193], v[178:179] op_sel_hi:[0,1]
	v_cvt_pk_bf16_f32 v36, v36, v37
	v_cvt_pk_bf16_f32 v37, v38, v39
	ds_write_b64 v206, v[36:37]
	v_pk_mul_f32 v[40:41], v[192:193], v[172:173] op_sel_hi:[0,1]
	v_pk_mul_f32 v[42:43], v[192:193], v[174:175] op_sel_hi:[0,1]
	v_cvt_pk_bf16_f32 v40, v40, v41
	v_cvt_pk_bf16_f32 v41, v42, v43
	ds_write_b64 v206, v[40:41] offset:32
	v_pk_mul_f32 v[36:37], v[192:193], v[168:169] op_sel_hi:[0,1]
	v_pk_mul_f32 v[38:39], v[192:193], v[170:171] op_sel_hi:[0,1]
	v_cvt_pk_bf16_f32 v36, v36, v37
	v_cvt_pk_bf16_f32 v37, v38, v39
	ds_write_b64 v206, v[36:37] offset:64
	v_pk_mul_f32 v[40:41], v[192:193], v[164:165] op_sel_hi:[0,1]
	v_pk_mul_f32 v[42:43], v[192:193], v[166:167] op_sel_hi:[0,1]
	v_cvt_pk_bf16_f32 v40, v40, v41
	v_cvt_pk_bf16_f32 v41, v42, v43
	ds_write_b64 v206, v[40:41] offset:96
	v_pk_mul_f32 v[36:37], v[192:193], v[160:161] op_sel_hi:[0,1]
	v_pk_mul_f32 v[38:39], v[192:193], v[162:163] op_sel_hi:[0,1]
	v_cvt_pk_bf16_f32 v36, v36, v37
	v_cvt_pk_bf16_f32 v37, v38, v39
	ds_write_b64 v206, v[36:37] offset:128
	v_pk_mul_f32 v[40:41], v[192:193], v[156:157] op_sel_hi:[0,1]
	v_pk_mul_f32 v[42:43], v[192:193], v[158:159] op_sel_hi:[0,1]
	v_cvt_pk_bf16_f32 v40, v40, v41
	v_cvt_pk_bf16_f32 v41, v42, v43
	ds_write_b64 v206, v[40:41] offset:160
	v_pk_mul_f32 v[36:37], v[192:193], v[152:153] op_sel_hi:[0,1]
	v_pk_mul_f32 v[38:39], v[192:193], v[154:155] op_sel_hi:[0,1]
	v_cvt_pk_bf16_f32 v36, v36, v37
	v_cvt_pk_bf16_f32 v37, v38, v39
	ds_write_b64 v206, v[36:37] offset:192
	v_pk_mul_f32 v[40:41], v[192:193], v[148:149] op_sel_hi:[0,1]
	v_pk_mul_f32 v[42:43], v[192:193], v[150:151] op_sel_hi:[0,1]
	v_cvt_pk_bf16_f32 v40, v40, v41
	v_cvt_pk_bf16_f32 v41, v42, v43
	ds_write_b64 v206, v[40:41] offset:224
	v_pk_mul_f32 v[36:37], v[192:193], v[144:145] op_sel_hi:[0,1]
	v_pk_mul_f32 v[38:39], v[192:193], v[146:147] op_sel_hi:[0,1]
	v_cvt_pk_bf16_f32 v36, v36, v37
	v_cvt_pk_bf16_f32 v37, v38, v39
	ds_write_b64 v206, v[36:37] offset:256
	v_pk_mul_f32 v[40:41], v[192:193], v[140:141] op_sel_hi:[0,1]
	v_pk_mul_f32 v[42:43], v[192:193], v[142:143] op_sel_hi:[0,1]
	v_cvt_pk_bf16_f32 v40, v40, v41
	v_cvt_pk_bf16_f32 v41, v42, v43
	ds_write_b64 v206, v[40:41] offset:288
	v_pk_mul_f32 v[36:37], v[192:193], v[136:137] op_sel_hi:[0,1]
	v_pk_mul_f32 v[38:39], v[192:193], v[138:139] op_sel_hi:[0,1]
	v_cvt_pk_bf16_f32 v36, v36, v37
	v_cvt_pk_bf16_f32 v37, v38, v39
	ds_write_b64 v206, v[36:37] offset:320
	v_pk_mul_f32 v[40:41], v[192:193], v[132:133] op_sel_hi:[0,1]
	v_pk_mul_f32 v[42:43], v[192:193], v[134:135] op_sel_hi:[0,1]
	v_cvt_pk_bf16_f32 v40, v40, v41
	v_cvt_pk_bf16_f32 v41, v42, v43
	ds_write_b64 v206, v[40:41] offset:352
	v_pk_mul_f32 v[36:37], v[192:193], v[128:129] op_sel_hi:[0,1]
	v_pk_mul_f32 v[38:39], v[192:193], v[130:131] op_sel_hi:[0,1]
	v_cvt_pk_bf16_f32 v36, v36, v37
	v_cvt_pk_bf16_f32 v37, v38, v39
	ds_write_b64 v206, v[36:37] offset:384
	v_pk_mul_f32 v[40:41], v[192:193], v[124:125] op_sel_hi:[0,1]
	v_pk_mul_f32 v[42:43], v[192:193], v[126:127] op_sel_hi:[0,1]
	v_cvt_pk_bf16_f32 v40, v40, v41
	v_cvt_pk_bf16_f32 v41, v42, v43
	ds_write_b64 v206, v[40:41] offset:416
	v_pk_mul_f32 v[36:37], v[192:193], v[120:121] op_sel_hi:[0,1]
	v_pk_mul_f32 v[38:39], v[192:193], v[122:123] op_sel_hi:[0,1]
	v_cvt_pk_bf16_f32 v36, v36, v37
	v_cvt_pk_bf16_f32 v37, v38, v39
	ds_write_b64 v206, v[36:37] offset:448
	v_pk_mul_f32 v[40:41], v[192:193], v[116:117] op_sel_hi:[0,1]
	v_pk_mul_f32 v[42:43], v[192:193], v[118:119] op_sel_hi:[0,1]
	v_cvt_pk_bf16_f32 v40, v40, v41
	v_cvt_pk_bf16_f32 v41, v42, v43
	ds_write_b64 v206, v[40:41] offset:480
	s_waitcnt lgkmcnt(0)
	ds_read_b128 v[44:47], v205
	ds_read_b128 v[48:51], v205 offset:1056
	ds_read_b128 v[52:55], v205 offset:2112
	ds_read_b128 v[56:59], v205 offset:3168
	ds_read_b128 v[60:63], v205 offset:4224
	ds_read_b128 v[64:67], v205 offset:5280
	ds_read_b128 v[68:71], v205 offset:6336
	ds_read_b128 v[72:75], v205 offset:7392
	v_add_u32_e32 v217, 0x1000, v204
	v_add_u32_e32 v218, 0x2000, v204
	v_add_u32_e32 v219, 0x3000, v204
	v_add_u32_e32 v220, 0x4000, v204
	v_add_u32_e32 v221, 0x5000, v204
	v_add_u32_e32 v222, 0x6000, v204
	v_add_u32_e32 v223, 0x7000, v204
	s_waitcnt lgkmcnt(7)
	global_store_dwordx4 v204, v[44:47], s[8:9]
	s_waitcnt lgkmcnt(6)
	global_store_dwordx4 v217, v[48:51], s[8:9]
	s_waitcnt lgkmcnt(5)
	global_store_dwordx4 v218, v[52:55], s[8:9]
	s_waitcnt lgkmcnt(4)
	global_store_dwordx4 v219, v[56:59], s[8:9]
	s_waitcnt lgkmcnt(3)
	global_store_dwordx4 v220, v[60:63], s[8:9]
	s_waitcnt lgkmcnt(2)
	global_store_dwordx4 v221, v[64:67], s[8:9]
	s_waitcnt lgkmcnt(1)
	global_store_dwordx4 v222, v[68:71], s[8:9]
	s_waitcnt lgkmcnt(0)
	global_store_dwordx4 v223, v[72:75], s[8:9]
	s_branch .LBB0_1083
